# gdn_scan: alternate the two 4-wave groups per chunk step (f32 state handed over through LDS) so operand prefetch runs 4 steps ahead
# baseline (speedup 1.0000x reference)
; #define LAS __attribute__((address_space(3)))
; DI void lds_barrier() { asm volatile("s_waitcnt lgkmcnt(0)" ::: "memory"); __builtin_amdgcn_s_barrier(); asm volatile("" ::: "memory"); }
; #define TIE8(NSTR, a, b) asm volatile("s_waitcnt vmcnt(" NSTR ")" : "+v"(a[0]), "+v"(a[1]), "+v"(a[2]), "+v"(a[3]), "+v"(b[0]), "+v"(b[1]), "+v"(b[2]), "+v"(b[3]) :: "memory")
; #define SCAN_LOAD_A1(A1_, n_) do { const unsigned char* f_ = fb + (size_t)(n_) * FRAG_ITEM + a1off; \
;         _Pragma("unroll") for (int s = 0; s < 8; ++s) GLD16(A1_[s], f_ + s * 1024); } while (0)
; #define SCAN_LOAD_X(KT_, X_, n_) do { const unsigned char* f_ = fb + (size_t)(n_) * FRAG_ITEM + ktoff; const unsigned char* x_ = xbase + (size_t)(n_) * xitem; \
;         _Pragma("unroll") for (int s = 0; s < 4; ++s) GLD16(KT_[s], f_ + s * 1024); \
;         _Pragma("unroll") for (int s = 0; s < 4; ++s) GLD16(X_[s], x_ + s * 1024); } while (0)
; DI void gdn_scan(LAS unsigned char* lds, PP p, int wg) {
;     ...
;     LAS u32x4* Simg = (LAS u32x4*)lds;
;     LAS u32x4* Vimg = (LAS u32x4*)(lds + 8192);
;     LAS bf16_t* Oimg = (LAS bf16_t*)(lds + 12288);
;     f32x16 S; for (int i = 0; i < 16; ++i) S[i] = 0.f;
;     if (act) { Simg[(2 * rt) * 64 + lane] = (u32x4){0u, 0u, 0u, 0u}; Simg[(2 * rt + 1) * 64 + lane] = (u32x4){0u, 0u, 0u, 0u}; }
;     lds_barrier();
;     const unsigned char* fb = p->ws + O_A + (size_t)(hd * 256) * FRAG_ITEM;
;     const unsigned char* ub = p->ws + O_UFR + (size_t)(hd * 256) * UFR_ITEM;
;     const float* GL = (const float*)(p->ws + O_GL) + hd * 256;
;     bf16_t* obf = (bf16_t*)(p->ws + O_OBF);
;     const size_t a1off = (rt < 2 ? 0 : 16384) + (size_t)((rt & 1) * 8) * 1024 + lane * 16;
;     const size_t ktoff = 40960 + (size_t)(rt * 4) * 1024 + lane * 16;
;     const unsigned char* xbase = rt >= 2 ? fb + 32768 + (size_t)((rt & 1) * 4) * 1024 + lane * 16 : ub + (size_t)((rt & 1) * 4 + cb) * 4096 + lane * 16;
;     const size_t xitem = rt >= 2 ? FRAG_ITEM : UFR_ITEM;
;     ...
;     u32x4 A1a[8], A1b[8], KTa[4], KTb[4], Xa[4], Xb[4];
;     const float glr0 = GL[lane], glr1 = GL[64 + lane], glr2 = GL[128 + lane], glr3 = GL[192 + lane];
;     asm volatile("s_waitcnt vmcnt(0)" ::: "memory");
;     SCAN_LOAD_A1(A1a, 0); SCAN_LOAD_X(KTa, Xa, 0); SCAN_LOAD_A1(A1b, 1); SCAN_LOAD_X(KTb, Xb, 1);
;     TIE8("0", A1a, (A1a + 4)); TIE8("0", KTa, Xa); TIE8("0", A1b, (A1b + 4)); TIE8("0", KTb, Xb);
.LBB0_355:
	s_or_b64 exec, exec, s[2:3]
	s_and_b32 s30, s63, 7
	s_ashr_i32 s31, s63, 3
	s_lshl_b32 s34, s30, 8
	s_mul_i32 s2, s30, 0xe00000
	s_add_u32 s2, s94, s2
	s_waitcnt lgkmcnt(0)
	s_barrier
	s_addc_u32 s3, s95, 0
	s_add_u32 s20, s2, 0xb100000
	s_addc_u32 s21, s3, 0
	v_bfe_u32 v7, v4, 6, 1
	v_cmp_lt_u32_e64 s[24:25], 1, v5
	v_cmp_gt_u32_e64 s[26:27], 2, v5
	s_and_saveexec_b64 s[2:3], s[26:27]
	s_xor_b64 s[2:3], exec, s[2:3]
	s_lshl_b32 s28, s34, 15
	v_lshl_add_u32 v0, v7, 2, s31
	s_add_u32 s28, s94, s28
	v_ashrrev_i32_e32 v1, 31, v0
	s_addc_u32 s29, s95, 0
	v_lshlrev_b64 v[0:1], 12, v[0:1]
	v_lshl_add_u64 v[0:1], s[28:29], 0, v[0:1]
	s_mov_b64 s[28:29], 0x12100000
	v_lshl_add_u64 v[0:1], v[0:1], 0, s[28:29]
	s_or_saveexec_b64 s[2:3], s[2:3]
	v_mov_b64_e32 v[202:203], 0x8000
	s_xor_b64 exec, exec, s[2:3]
	v_lshlrev_b32_e32 v0, 12, v7
	v_mov_b32_e32 v1, v3
	v_lshl_add_u64 v[0:1], s[20:21], 0, v[0:1]
	s_mov_b64 s[28:29], 0x8000
	v_lshl_add_u64 v[0:1], v[0:1], 0, s[28:29]
	v_mov_b64_e32 v[202:203], 0xe000
	s_or_b64 exec, exec, s[2:3]
	s_lshl_b32 s2, s34, 2
	s_add_u32 s38, s94, s2
	s_addc_u32 s39, s95, 0
	v_lshl_add_u64 v[204:205], v[0:1], 0, v[2:3]
	v_lshlrev_b32_e32 v0, 2, v6
	v_mov_b32_e32 v1, v3
	v_lshl_add_u64 v[0:1], s[38:39], 0, v[0:1]
	s_mov_b64 s[38:39], 0x2da20000
	s_mov_b32 s35, 0x2da20000
	v_lshl_add_u64 v[12:13], v[0:1], 0, s[38:39]
	v_add_co_u32_e32 v0, vcc, s35, v0
	v_cmp_gt_u32_e64 s[28:29], 2, v5
	s_nop 0
	v_addc_co_u32_e32 v1, vcc, 0, v1, vcc
	global_load_dword v231, v[0:1], off
	global_load_dword v232, v[12:13], off offset:256
	global_load_dword v233, v[12:13], off offset:512
	global_load_dword v234, v[12:13], off offset:768
	v_mov_b32_e32 v8, 0x4000
	v_cndmask_b32_e64 v8, v8, 0, s[28:29]
	v_lshlrev_b32_e32 v7, 13, v7
	v_or3_b32 v8, v7, v2, v8
	v_mov_b32_e32 v9, v3
	s_waitcnt vmcnt(0)
	v_lshl_add_u64 v[206:207], s[20:21], 0, v[8:9]
	global_load_dwordx4 v[72:75], v[206:207], off
	s_mov_b64 s[50:51], 0x400
	v_lshl_add_u64 v[0:1], v[206:207], 0, s[50:51]
	global_load_dwordx4 v[68:71], v[0:1], off
	s_mov_b64 s[52:53], 0x800
	v_lshl_add_u64 v[0:1], v[206:207], 0, s[52:53]
	global_load_dwordx4 v[88:91], v[0:1], off
	s_mov_b64 s[54:55], 0xc00
	v_lshl_add_u64 v[0:1], v[206:207], 0, s[54:55]
	global_load_dwordx4 v[84:87], v[0:1], off
	s_mov_b64 s[38:39], 0x1000
	v_lshl_add_u64 v[0:1], v[206:207], 0, s[38:39]
	global_load_dwordx4 v[100:103], v[0:1], off
	s_mov_b64 s[44:45], 0x1400
	v_lshl_add_u64 v[0:1], v[206:207], 0, s[44:45]
	global_load_dwordx4 v[92:95], v[0:1], off
	s_mov_b64 s[40:41], 0x1800
	v_lshl_or_b32 v7, v5, 12, v2
	v_lshl_add_u64 v[0:1], v[206:207], 0, s[40:41]
	global_load_dwordx4 v[152:155], v[0:1], off
	s_mov_b64 s[48:49], 0x1c00
	v_add_u32_e32 v10, 0xa000, v7
	v_mov_b32_e32 v11, v3
	v_lshl_add_u64 v[0:1], v[206:207], 0, s[48:49]
	global_load_dwordx4 v[144:147], v[0:1], off
	v_lshl_add_u64 v[208:209], s[20:21], 0, v[10:11]
	global_load_dwordx4 v[112:115], v[208:209], off
	v_lshl_add_u64 v[0:1], v[208:209], 0, s[50:51]
	global_load_dwordx4 v[104:107], v[0:1], off
	v_lshl_add_u64 v[0:1], v[208:209], 0, s[52:53]
	global_load_dwordx4 v[80:83], v[0:1], off
	v_lshl_add_u64 v[0:1], v[208:209], 0, s[54:55]
	global_load_dwordx4 v[64:67], v[0:1], off
	s_add_u32 s2, s94, 0x28100000
	global_load_dwordx4 v[120:123], v[204:205], off
	s_addc_u32 s3, s95, 0
	v_lshl_add_u64 v[0:1], v[204:205], 0, s[50:51]
	global_load_dwordx4 v[108:111], v[0:1], off
	v_lshl_add_u64 v[0:1], v[204:205], 0, s[52:53]
	global_load_dwordx4 v[96:99], v[0:1], off
	s_add_u32 s20, s20, 0xe000
	v_lshl_add_u64 v[0:1], v[204:205], 0, s[54:55]
	global_load_dwordx4 v[76:79], v[0:1], off
	s_addc_u32 s21, s21, 0
	v_lshl_add_u64 v[0:1], s[20:21], 0, v[8:9]
	global_load_dwordx4 v[128:131], v[0:1], off
	v_lshl_add_u64 v[8:9], v[0:1], 0, s[50:51]
	global_load_dwordx4 v[124:127], v[8:9], off
	v_lshl_add_u64 v[8:9], v[0:1], 0, s[52:53]
	global_load_dwordx4 v[148:151], v[8:9], off
	v_lshl_add_u64 v[8:9], v[0:1], 0, s[54:55]
	global_load_dwordx4 v[132:135], v[8:9], off
	v_lshl_add_u64 v[8:9], v[0:1], 0, s[38:39]
	global_load_dwordx4 v[160:163], v[8:9], off
	v_lshl_add_u64 v[8:9], v[0:1], 0, s[44:45]
	global_load_dwordx4 v[156:159], v[8:9], off
	v_lshl_add_u64 v[8:9], v[0:1], 0, s[40:41]
	global_load_dwordx4 v[188:191], v[8:9], off
	v_lshl_add_u64 v[0:1], v[0:1], 0, s[48:49]
	global_load_dwordx4 v[184:187], v[0:1], off
	v_lshl_add_u64 v[0:1], s[20:21], 0, v[10:11]
	global_load_dwordx4 v[176:179], v[0:1], off
	v_lshl_add_u64 v[10:11], v[0:1], 0, s[50:51]
	global_load_dwordx4 v[168:171], v[10:11], off
	v_lshl_add_u64 v[10:11], v[0:1], 0, s[52:53]
	global_load_dwordx4 v[136:139], v[10:11], off
	v_lshl_add_u64 v[8:9], v[204:205], 0, v[202:203]
	v_lshl_add_u64 v[0:1], v[0:1], 0, s[54:55]
	global_load_dwordx4 v[116:119], v[0:1], off
	global_load_dwordx4 v[180:183], v[8:9], off
	v_lshl_add_u64 v[0:1], v[8:9], 0, s[50:51]
	global_load_dwordx4 v[172:175], v[0:1], off
	v_lshl_add_u64 v[0:1], v[8:9], 0, s[52:53]
	global_load_dwordx4 v[164:167], v[0:1], off
	v_lshl_add_u64 v[0:1], v[8:9], 0, s[54:55]
	global_load_dwordx4 v[140:143], v[0:1], off
	v_add_u32_e32 v0, -2, v5
	s_movk_i32 s20, 0xa00
	s_add_u32 s34, s2, s34
	v_add_u32_e32 v203, 0, v2
	v_mad_i32_i24 v0, v0, s20, 0
	v_lshlrev_b32_e32 v2, 4, v4
	s_addc_u32 s35, s3, 0
	s_lshl_b32 s20, s31, 5
	v_and_b32_e32 v7, 31, v4
	v_and_b32_e32 v2, 48, v2
	s_ashr_i32 s21, s20, 31
	v_lshl_add_u32 v235, v7, 1, v0
	v_add_u32_e32 v236, v0, v2
	s_lshl_b64 s[20:21], s[20:21], 1
	v_lshrrev_b32_e32 v0, 2, v6
	s_add_u32 s34, s34, s20
	v_mul_u32_u24_e32 v238, 0x50, v0
	v_lshl_or_b32 v5, v5, 5, v0
	v_and_b32_e32 v0, 3, v4
	v_lshrrev_b32_e32 v1, 3, v4
	s_addc_u32 s35, s35, s21
	v_lshlrev_b32_e32 v0, 4, v0
	s_waitcnt vmcnt(0)
; DI void lds_barrier() { asm volatile("s_waitcnt lgkmcnt(0)" ::: "memory"); __builtin_amdgcn_s_barrier(); asm volatile("" ::: "memory"); }
; #define TIE8(NSTR, a, b) asm volatile("s_waitcnt vmcnt(" NSTR ")" : "+v"(a[0]), "+v"(a[1]), "+v"(a[2]), "+v"(a[3]), "+v"(b[0]), "+v"(b[1]), "+v"(b[2]), "+v"(b[3]) :: "memory")
; #define SCAN_LOAD_A1(A1_, n_) do { const unsigned char* f_ = fb + (size_t)(n_) * FRAG_ITEM + a1off; \
;         _Pragma("unroll") for (int s = 0; s < 8; ++s) GLD16(A1_[s], f_ + s * 1024); } while (0)
; #define SCAN_LOAD_X(KT_, X_, n_) do { const unsigned char* f_ = fb + (size_t)(n_) * FRAG_ITEM + ktoff; const unsigned char* x_ = xbase + (size_t)(n_) * xitem; \
;         _Pragma("unroll") for (int s = 0; s < 4; ++s) GLD16(KT_[s], f_ + s * 1024); \
;         _Pragma("unroll") for (int s = 0; s < 4; ++s) GLD16(X_[s], x_ + s * 1024); } while (0)
; DI void gdn_scan(LAS unsigned char* lds, PP p, int wg) {
;     ...
;     f32x16 S; for (int i = 0; i < 16; ++i) S[i] = 0.f;
;     if (act) { Simg[(2 * rt) * 64 + lane] = (u32x4){0u, 0u, 0u, 0u}; Simg[(2 * rt + 1) * 64 + lane] = (u32x4){0u, 0u, 0u, 0u}; }
;     lds_barrier();
;     const unsigned char* fb = p->ws + O_A + (size_t)(hd * 256) * FRAG_ITEM;
;     const unsigned char* ub = p->ws + O_UFR + (size_t)(hd * 256) * UFR_ITEM;
;     const float* GL = (const float*)(p->ws + O_GL) + hd * 256;
;     bf16_t* obf = (bf16_t*)(p->ws + O_OBF);
;     const size_t a1off = (rt < 2 ? 0 : 16384) + (size_t)((rt & 1) * 8) * 1024 + lane * 16;
;     const size_t ktoff = 40960 + (size_t)(rt * 4) * 1024 + lane * 16;
;     const unsigned char* xbase = rt >= 2 ? fb + 32768 + (size_t)((rt & 1) * 4) * 1024 + lane * 16 : ub + (size_t)((rt & 1) * 4 + cb) * 4096 + lane * 16;
;     const size_t xitem = rt >= 2 ? FRAG_ITEM : UFR_ITEM;
;     ...
;     u32x4 A1a[8], A1b[8], KTa[4], KTb[4], Xa[4], Xb[4];
;     const float glr0 = GL[lane], glr1 = GL[64 + lane], glr2 = GL[128 + lane], glr3 = GL[192 + lane];
;     asm volatile("s_waitcnt vmcnt(0)" ::: "memory");
;     SCAN_LOAD_A1(A1a, 0); SCAN_LOAD_X(KTa, Xa, 0); SCAN_LOAD_A1(A1b, 1); SCAN_LOAD_X(KTb, Xb, 1);
;     TIE8("0", A1a, (A1a + 4)); TIE8("0", KTa, Xa); TIE8("0", A1b, (A1b + 4)); TIE8("0", KTb, Xb);
	v_and_b32_e32 v1, 4, v1
	v_lshl_add_u64 v[210:211], s[34:35], 0, v[2:3]
	v_lshl_or_b32 v2, s30, 8, v0
	v_lshlrev_b32_e32 v6, 11, v5
	s_waitcnt vmcnt(0)
	v_mul_u32_u24_e32 v237, 0x50, v1
	v_subrev_u32_e32 v212, 64, v5
	v_lshl_add_u64 v[0:1], v[2:3], 0, s[20:21]
	v_or_b32_e32 v4, 0x8000, v6
	v_mov_b32_e32 v5, v3
	s_waitcnt vmcnt(0)
	v_lshl_add_u64 v[0:1], v[0:1], 0, v[4:5]
	s_waitcnt vmcnt(0)
	v_lshl_add_u64 v[214:215], s[2:3], 0, v[0:1]
	s_add_u32 s2, s2, s20
	v_mov_b32_e32 v30, v3
	v_mov_b32_e32 v31, v3
	v_or_b32_e32 v2, v2, v6
	s_addc_u32 s3, s3, s21
	v_mov_b32_e32 v16, v3
	v_mov_b32_e32 v17, v3
	v_mov_b32_e32 v18, v3
	v_mov_b32_e32 v19, v3
	v_mov_b32_e32 v20, v3
	v_mov_b32_e32 v21, v3
	v_mov_b32_e32 v22, v3
	v_mov_b32_e32 v23, v3
	v_mov_b32_e32 v24, v3
	v_mov_b32_e32 v25, v3
	v_mov_b32_e32 v26, v3
	v_mov_b32_e32 v27, v3
	v_mov_b32_e32 v28, v3
	v_mov_b32_e32 v29, v3
	v_mov_b64_e32 v[46:47], v[30:31]
	s_mov_b32 s37, 0
	s_mov_b64 s[42:43], 0x1000
	s_mov_b64 s[58:59], 0x1400
	s_mov_b64 s[44:45], 0x1800
	s_mov_b64 s[60:61], 0x1c00
	s_mov_b64 s[48:49], 0x400
	s_mov_b64 s[50:51], 0x800
	s_mov_b64 s[52:53], 0xc00
	v_lshl_add_u64 v[216:217], s[2:3], 0, v[2:3]
	v_mov_b64_e32 v[44:45], v[28:29]
	v_mov_b64_e32 v[42:43], v[26:27]
	v_mov_b64_e32 v[40:41], v[24:25]
	v_mov_b64_e32 v[38:39], v[22:23]
	v_mov_b64_e32 v[36:37], v[20:21]
	v_mov_b64_e32 v[34:35], v[18:19]
	v_mov_b64_e32 v[32:33], v[16:17]
	s_waitcnt vmcnt(0)
	s_andn2_b64 exec, exec, s[22:23]
	s_cbranch_execz .Lscan_gB_skip
	s_mov_b64 s[2:3], 0x1c000
	s_mov_b64 s[20:21], 0x1000
	v_lshl_add_u64 v[248:249], v[206:207], 0, s[2:3]
	global_load_dwordx4 v[72:75], v[248:249], off
	global_load_dwordx4 v[68:71], v[248:249], off offset:1024
	global_load_dwordx4 v[88:91], v[248:249], off offset:2048
	global_load_dwordx4 v[84:87], v[248:249], off offset:3072
	v_lshl_add_u64 v[250:251], v[248:249], 0, s[20:21]
	global_load_dwordx4 v[100:103], v[250:251], off
	global_load_dwordx4 v[92:95], v[250:251], off offset:1024
	global_load_dwordx4 v[152:155], v[250:251], off offset:2048
	global_load_dwordx4 v[144:147], v[250:251], off offset:3072
	v_lshl_add_u64 v[248:249], v[208:209], 0, s[2:3]
	global_load_dwordx4 v[112:115], v[248:249], off
	global_load_dwordx4 v[104:107], v[248:249], off offset:1024
	global_load_dwordx4 v[80:83], v[248:249], off offset:2048
	global_load_dwordx4 v[64:67], v[248:249], off offset:3072
	v_mul_u32_u24_e32 v248, 2, v202
	v_mov_b32_e32 v249, 0
	v_lshl_add_u64 v[248:249], v[248:249], 0, v[204:205]
	global_load_dwordx4 v[120:123], v[248:249], off
	global_load_dwordx4 v[108:111], v[248:249], off offset:1024
	global_load_dwordx4 v[96:99], v[248:249], off offset:2048
	global_load_dwordx4 v[76:79], v[248:249], off offset:3072
.Lscan_gB_skip:
	s_mov_b64 exec, -1
	s_and_b64 exec, exec, s[22:23]
	s_cbranch_execz .Lscan_gA_skip
	s_mov_b64 s[2:3], 0x2a000
	s_mov_b64 s[20:21], 0x1000
	v_lshl_add_u64 v[248:249], v[206:207], 0, s[2:3]
	global_load_dwordx4 v[128:131], v[248:249], off
	global_load_dwordx4 v[124:127], v[248:249], off offset:1024
	global_load_dwordx4 v[148:151], v[248:249], off offset:2048
	global_load_dwordx4 v[132:135], v[248:249], off offset:3072
	v_lshl_add_u64 v[250:251], v[248:249], 0, s[20:21]
	global_load_dwordx4 v[160:163], v[250:251], off
	global_load_dwordx4 v[156:159], v[250:251], off offset:1024
	global_load_dwordx4 v[188:191], v[250:251], off offset:2048
	global_load_dwordx4 v[184:187], v[250:251], off offset:3072
	v_lshl_add_u64 v[248:249], v[208:209], 0, s[2:3]
	global_load_dwordx4 v[176:179], v[248:249], off
	global_load_dwordx4 v[168:171], v[248:249], off offset:1024
	global_load_dwordx4 v[136:139], v[248:249], off offset:2048
	global_load_dwordx4 v[116:119], v[248:249], off offset:3072
	v_mul_u32_u24_e32 v248, 3, v202
	v_mov_b32_e32 v249, 0
	v_lshl_add_u64 v[248:249], v[248:249], 0, v[204:205]
	global_load_dwordx4 v[180:183], v[248:249], off
	global_load_dwordx4 v[172:175], v[248:249], off offset:1024
	global_load_dwordx4 v[164:167], v[248:249], off offset:2048
	global_load_dwordx4 v[140:143], v[248:249], off offset:3072
.Lscan_gA_skip:
	s_mov_b64 exec, -1
	v_lshrrev_b32_e32 v252, 6, v201
	v_and_b32_e32 v252, 3, v252
	v_lshlrev_b32_e32 v252, 12, v252
	v_and_b32_e32 v253, 63, v201
	v_lshl_add_u32 v253, v253, 4, v252
	v_add_u32_e32 v253, 0x8000, v253
	v_mov_b32_e32 v248, 0
	v_mov_b32_e32 v249, 0
	v_mov_b32_e32 v250, 0
	v_mov_b32_e32 v251, 0
	ds_write_b128 v253, v[248:251]
	ds_write_b128 v253, v[248:251] offset:1024
	ds_write_b128 v253, v[248:251] offset:2048
	ds_write_b128 v253, v[248:251] offset:3072
	s_waitcnt vmcnt(0) lgkmcnt(0)
	s_barrier
	s_branch .LBB0_362
.LBB0_360:
	s_or_b64 exec, exec, s[2:3]
	v_cvt_pk_bf16_f32 v4, v32, v33
	v_cvt_pk_bf16_f32 v5, v34, v35
	v_cvt_pk_bf16_f32 v6, v36, v37
	v_cvt_pk_bf16_f32 v7, v38, v39
	v_add_u32_e32 v0, v203, v230
	ds_write_b128 v0, v[4:7]
	v_cvt_pk_bf16_f32 v4, v40, v41
	v_cvt_pk_bf16_f32 v5, v42, v43
	v_cvt_pk_bf16_f32 v6, v44, v45
	v_cvt_pk_bf16_f32 v7, v46, v47
	ds_write_b128 v0, v[4:7] offset:1024
	ds_write_b128 v253, v[32:35]
	ds_write_b128 v253, v[36:39] offset:1024
	ds_write_b128 v253, v[40:43] offset:2048
	ds_write_b128 v253, v[44:47] offset:3072

.LBB0_362:
	s_cmp_lt_u32 s37, 64
	s_cselect_b64 vcc, -1, 0
	s_cmpk_lt_u32 s37, 0x80
	s_cselect_b64 s[30:31], -1, 0
	s_cmpk_lt_u32 s37, 0xc0
	s_cselect_b64 s[34:35], -1, 0
	v_cndmask_b32_e64 v0, v234, v233, s[34:35]
	s_cmpk_gt_u32 s37, 0xfd
	v_cndmask_b32_e64 v0, v0, v232, s[30:31]
	s_cselect_b64 s[20:21], -1, 0
	s_add_i32 s36, s37, 2
	v_cndmask_b32_e32 v0, v0, v231, vcc
	s_cmpk_lt_u32 s37, 0xfe
	v_readlane_b32 s2, v0, s37
	s_cselect_b32 s38, s36, 0xff
	s_add_i32 s38, s37, 4
	s_min_u32 s38, s38, 0xff
	s_and_saveexec_b64 s[30:31], s[22:23]
	s_cbranch_execz .LBB0_372
	ds_read_b128 v[32:35], v253
	ds_read_b128 v[36:39], v253 offset:1024
	ds_read_b128 v[40:43], v253 offset:2048
	ds_read_b128 v[44:47], v253 offset:3072
	ds_read_b128 v[4:7], v203
	ds_read_b128 v[8:11], v203 offset:1024
	ds_read_b128 v[12:15], v203 offset:2048
	ds_read_b128 v[16:19], v203 offset:3072
	ds_read_b128 v[20:23], v203 offset:4096
	ds_read_b128 v[24:27], v203 offset:5120
	ds_read_b128 v[28:31], v203 offset:6144
	s_and_saveexec_b64 s[34:35], s[26:27]
	s_xor_b64 s[34:35], exec, s[34:35]
	s_cbranch_execz .LBB0_365
	s_waitcnt vmcnt(24)

.LBB0_383:
	s_or_b64 exec, exec, s[2:3]
	v_cvt_pk_bf16_f32 v4, v32, v33
	v_cvt_pk_bf16_f32 v5, v34, v35
	v_cvt_pk_bf16_f32 v6, v36, v37
	v_cvt_pk_bf16_f32 v7, v38, v39
	v_add_u32_e32 v1, v203, v230
	ds_write_b128 v1, v[4:7]
	v_cvt_pk_bf16_f32 v4, v40, v41
	v_cvt_pk_bf16_f32 v5, v42, v43
	v_cvt_pk_bf16_f32 v6, v44, v45
	v_cvt_pk_bf16_f32 v7, v46, v47
	ds_write_b128 v1, v[4:7] offset:1024
	ds_write_b128 v253, v[32:35]
	ds_write_b128 v253, v[36:39] offset:1024
	ds_write_b128 v253, v[40:43] offset:2048
	ds_write_b128 v253, v[44:47] offset:3072
.LBB0_384:
	s_or_b64 exec, exec, s[30:31]
	s_waitcnt lgkmcnt(0)
	s_barrier
	s_not_b64 s[22:23], s[22:23]
	s_min_u32 s3, s37, 0xfa
	s_add_i32 s2, s37, 1
	v_readlane_b32 s2, v0, s2
	s_add_i32 s37, s3, 5
	s_mul_i32 s56, s37, 0xe000
	s_and_saveexec_b64 s[30:31], s[22:23]
	s_cbranch_execz .LBB0_394
	ds_read_b128 v[32:35], v253
	ds_read_b128 v[36:39], v253 offset:1024
	ds_read_b128 v[40:43], v253 offset:2048
	ds_read_b128 v[44:47], v253 offset:3072
	ds_read_b128 v[4:7], v203
	ds_read_b128 v[8:11], v203 offset:1024
	ds_read_b128 v[12:15], v203 offset:2048
	ds_read_b128 v[16:19], v203 offset:3072
	ds_read_b128 v[20:23], v203 offset:4096
	ds_read_b128 v[24:27], v203 offset:5120
	ds_read_b128 v[28:31], v203 offset:6144
	s_and_saveexec_b64 s[34:35], s[26:27]
	s_xor_b64 s[34:35], exec, s[34:35]
	s_cbranch_execz .LBB0_387
	s_waitcnt vmcnt(24)
